# DF unit-end wait+barrier and second queue-resolve barrier dropped
# speedup vs baseline: 1.0035x; 1.0035x over previous
.LBB0_299:
.LBB0_300:
	s_mov_b64 s[2:3], 0

.LBB0_332:
	s_or_b64 exec, exec, s[2:3]
	s_waitcnt lgkmcnt(0)
	s_barrier
	ds_read_b32 v0, v229
	s_movk_i32 s2, 0x3ff
	s_waitcnt lgkmcnt(0)
	v_cmp_lt_i32_e32 vcc, s2, v0
	v_readfirstlane_b32 s97, v0
	s_mov_b64 s[2:3], -1
	s_cbranch_vccnz .LBB0_301
	s_cmpk_gt_i32 s97, 0x1ff
	s_cbranch_scc0 .LBB0_385
	s_add_i32 s2, s97, 0xfffffe00
	s_lshr_b32 s99, s2, 6
	s_sub_i32 s6, 7, s99
	s_bfe_u32 s3, s97, 0x30003
	s_lshl_b32 s66, s6, 8
	v_readlane_b32 s2, v254, 53
	s_and_b32 s4, s97, 7
	s_add_i32 s66, s66, s2
	s_lshl_b32 s2, s3, 21
	s_waitcnt vmcnt(1)
	v_mov_b32_e32 v82, v231
	v_writelane_b32 v255, s3, 49
	s_add_u32 s2, s78, s2
	s_addc_u32 s3, s79, 0
	v_and_b32_e32 v3, 31, v82
	v_writelane_b32 v255, s4, 50
	s_lshl_b32 s4, s4, 18
	v_ashrrev_i32_e32 v2, 5, v82
	v_or_b32_e32 v0, s66, v3
	s_add_u32 s2, s2, s4
	s_addc_u32 s3, s3, 0
	v_lshlrev_b64 v[4:5], 7, v[0:1]
	v_lshlrev_b32_e32 v114, 3, v2
	v_lshl_add_u64 v[4:5], s[2:3], 0, v[4:5]
	v_ashrrev_i32_e32 v115, 31, v114
	v_lshl_add_u64 v[4:5], v[114:115], 1, v[4:5]
	global_load_dwordx4 v[98:101], v[4:5], off
	global_load_dwordx4 v[102:105], v[4:5], off offset:32
	global_load_dwordx4 v[106:109], v[4:5], off offset:64
	global_load_dwordx4 v[110:113], v[4:5], off offset:96
	v_cmp_gt_i32_e32 vcc, 2, v82
	s_and_saveexec_b64 s[4:5], vcc
	v_lshl_add_u32 v4, v82, 5, s94
	ds_write_b32 v4, v1
	s_or_b64 exec, exec, s[4:5]
	v_ashrrev_i32_e32 v4, 3, v82
	v_readlane_b32 s4, v254, 54
	v_mov_b32_e32 v7, v1
	v_mov_b32_e32 v9, v1
	v_add_u32_e32 v4, s4, v4
	v_lshrrev_b32_e32 v5, 1, v4
	v_xor_b32_e32 v6, v5, v82
	v_lshlrev_b32_e32 v4, 6, v4
	v_ashrrev_i32_e32 v5, 31, v4
	v_lshlrev_b32_e32 v6, 4, v6
	v_lshl_add_u64 v[4:5], v[4:5], 1, s[2:3]
	v_and_b32_e32 v6, 0x70, v6
	v_lshl_add_u64 v[4:5], v[4:5], 0, v[6:7]
	s_mov_b64 s[4:5], 0x1000000
	v_lshl_add_u64 v[116:117], v[4:5], 0, s[4:5]
	v_add_u32_e32 v5, s30, v114
	v_lshrrev_b32_e32 v4, 2, v82
	v_and_or_b32 v5, v4, 7, v5
	v_lshlrev_b32_e32 v6, 3, v82
	v_and_b32_e32 v126, 24, v6
	v_lshlrev_b32_e32 v6, 6, v5
	v_ashrrev_i32_e32 v7, 31, v6
	v_lshl_add_u64 v[6:7], v[6:7], 1, s[2:3]
	v_lshlrev_b32_e32 v8, 1, v126
	v_lshl_add_u64 v[6:7], v[6:7], 0, v[8:9]
	s_mov_b64 s[4:5], 0x2000000
	v_lshl_add_u64 v[118:119], v[6:7], 0, s[4:5]
	s_lshl_b32 s4, s6, 2
	s_add_i32 s80, s0, s4
	s_add_i32 s4, s80, 1
	s_mov_b32 s5, s81
	s_lshl_b64 s[6:7], s[4:5], 13
	v_lshl_add_u64 v[6:7], v[116:117], 0, s[6:7]
	s_mov_b64 s[10:11], 0x1000
	v_readlane_b32 s8, v255, 8
	s_mov_b32 s5, m0
	s_mov_b32 m0, s8
	s_nop 0
	global_load_lds_dwordx4 v[6:7], off
	s_mov_b32 m0, s5
	v_lshl_add_u64 v[6:7], v[6:7], 0, s[10:11]
	v_readlane_b32 s8, v254, 56
	s_mov_b32 s5, m0
	s_mov_b32 m0, s8
	s_nop 0
	global_load_lds_dwordx4 v[6:7], off
	s_mov_b32 m0, s5
	v_lshl_add_u64 v[6:7], v[118:119], 0, s[6:7]
	v_readlane_b32 s6, v254, 57
	s_mov_b32 s5, m0
	s_mov_b32 m0, s6
	s_nop 0
	global_load_lds_dwordx4 v[6:7], off
	s_mov_b32 m0, s5
	v_readlane_b32 s6, v254, 58
	v_lshl_add_u64 v[6:7], v[6:7], 0, 64
	s_mov_b32 s5, m0
	s_mov_b32 m0, s6
	s_nop 0
	global_load_lds_dwordx4 v[6:7], off
	s_mov_b32 m0, s5
	s_lshl_b64 s[6:7], s[80:81], 13
	v_lshl_add_u64 v[6:7], v[116:117], 0, s[6:7]
	v_readlane_b32 s8, v254, 59
	s_mov_b32 s5, m0
	s_mov_b32 m0, s8
	s_nop 0
	global_load_lds_dwordx4 v[6:7], off
	s_mov_b32 m0, s5
	v_lshl_add_u64 v[6:7], v[6:7], 0, s[10:11]
	v_readlane_b32 s8, v254, 60
	s_mov_b32 s5, m0
	s_mov_b32 m0, s8
	s_nop 0
	global_load_lds_dwordx4 v[6:7], off
	s_mov_b32 m0, s5
	v_lshl_add_u64 v[6:7], v[118:119], 0, s[6:7]
	v_readlane_b32 s6, v254, 61
	s_mov_b32 s5, m0
	s_mov_b32 m0, s6
	s_nop 0
	global_load_lds_dwordx4 v[6:7], off
	s_mov_b32 m0, s5
	v_lshl_add_u64 v[6:7], v[6:7], 0, 64
	v_readlane_b32 s8, v254, 62
	s_mov_b32 s5, m0
	s_mov_b32 m0, s8
	s_nop 0
	global_load_lds_dwordx4 v[6:7], off
	s_mov_b32 m0, s5
	s_cmp_lg_u32 s4, 1
	s_mov_b64 s[78:79], 0x1000
	s_cselect_b64 s[6:7], -1, 0
	s_cmp_eq_u32 s4, 1
	s_cbranch_scc1 .LBB0_338
	s_add_i32 s80, s4, -2
	s_lshl_b64 s[8:9], s[80:81], 13
	v_lshl_add_u64 v[6:7], v[116:117], 0, s[8:9]
	v_readlane_b32 s10, v254, 63
	s_mov_b32 s5, m0
	s_mov_b32 m0, s10
	s_nop 0
	global_load_lds_dwordx4 v[6:7], off
	s_mov_b32 m0, s5
	v_lshl_add_u64 v[6:7], v[6:7], 0, s[78:79]
	v_readlane_b32 s10, v255, 0
	s_mov_b32 s5, m0
	s_mov_b32 m0, s10
	s_nop 0
	global_load_lds_dwordx4 v[6:7], off
	s_mov_b32 m0, s5
	v_lshl_add_u64 v[6:7], v[118:119], 0, s[8:9]
	v_readlane_b32 s8, v255, 1
	s_mov_b32 s5, m0
	s_mov_b32 m0, s8
	s_nop 0
	global_load_lds_dwordx4 v[6:7], off
	s_mov_b32 m0, s5
	v_lshl_add_u64 v[6:7], v[6:7], 0, 64
	v_readlane_b32 s8, v255, 2
	s_mov_b32 s5, m0
	s_mov_b32 m0, s8
	s_nop 0
	global_load_lds_dwordx4 v[6:7], off
	s_mov_b32 m0, s5
